# ln_router both layers: router-weight LDS fill via LDS-DMA (global_load_lds_dwordx4), no VGPR staging
# speedup vs baseline: 1.0059x; 1.0002x over previous
.LBB0_832:
	s_mov_b64 s[2:3], s[8:9]
	v_lshrrev_b32_e32 v168, 6, v2
	s_nop 0
	v_readfirstlane_b32 s98, v168
	s_lshl_b32 s98, s98, 10
	s_mov_b32 m0, s98
	s_nop 0
	global_load_lds_dwordx4 v4, s[2:3]
	s_add_u32 s2, s2, 0x1000
	s_addc_u32 s3, s3, 0
	s_add_u32 m0, s98, 0x1000
	s_nop 0
	global_load_lds_dwordx4 v4, s[2:3]
	s_add_u32 s2, s2, 0x1000
	s_addc_u32 s3, s3, 0
	s_add_u32 m0, s98, 0x2000
	s_nop 0
	global_load_lds_dwordx4 v4, s[2:3]
	s_add_u32 s2, s2, 0x1000
	s_addc_u32 s3, s3, 0
	s_add_u32 m0, s98, 0x3000
	s_nop 0
	global_load_lds_dwordx4 v4, s[2:3]
	s_add_u32 s2, s2, 0x1000
	s_addc_u32 s3, s3, 0
	s_add_u32 m0, s98, 0x4000
	s_nop 0
	global_load_lds_dwordx4 v4, s[2:3]
	s_add_u32 s2, s2, 0x1000
	s_addc_u32 s3, s3, 0
	s_add_u32 m0, s98, 0x5000
	s_nop 0
	global_load_lds_dwordx4 v4, s[2:3]
	s_add_u32 s2, s2, 0x1000
	s_addc_u32 s3, s3, 0
	s_add_u32 m0, s98, 0x6000
	s_nop 0
	global_load_lds_dwordx4 v4, s[2:3]
	s_add_u32 s2, s2, 0x1000
	s_addc_u32 s3, s3, 0
	s_add_u32 m0, s98, 0x7000
	s_nop 0
	global_load_lds_dwordx4 v4, s[2:3]
	s_add_u32 s2, s2, 0x1000
	s_addc_u32 s3, s3, 0
	s_add_u32 m0, s98, 0x8000
	s_nop 0
	global_load_lds_dwordx4 v4, s[2:3]
	s_add_u32 s2, s2, 0x1000
	s_addc_u32 s3, s3, 0
	s_add_u32 m0, s98, 0x9000
	s_nop 0
	global_load_lds_dwordx4 v4, s[2:3]
	s_add_u32 s2, s2, 0x1000
	s_addc_u32 s3, s3, 0
	s_add_u32 m0, s98, 0xa000
	s_nop 0
	global_load_lds_dwordx4 v4, s[2:3]
	s_add_u32 s2, s2, 0x1000
	s_addc_u32 s3, s3, 0
	s_add_u32 m0, s98, 0xb000
	s_nop 0
	global_load_lds_dwordx4 v4, s[2:3]
	s_add_u32 s2, s2, 0x1000
	s_addc_u32 s3, s3, 0
	s_add_u32 m0, s98, 0xc000
	s_nop 0
	global_load_lds_dwordx4 v4, s[2:3]
	s_add_u32 s2, s2, 0x1000
	s_addc_u32 s3, s3, 0
	s_add_u32 m0, s98, 0xd000
	s_nop 0
	global_load_lds_dwordx4 v4, s[2:3]
	s_add_u32 s2, s2, 0x1000
	s_addc_u32 s3, s3, 0
	s_add_u32 m0, s98, 0xe000
	s_nop 0
	global_load_lds_dwordx4 v4, s[2:3]
	s_add_u32 s2, s2, 0x1000
	s_addc_u32 s3, s3, 0
	s_add_u32 m0, s98, 0xf000
	s_nop 0
	global_load_lds_dwordx4 v4, s[2:3]
	s_waitcnt vmcnt(0)

.LBB0_1865:
	s_mov_b64 s[4:5], s[2:3]
	v_lshrrev_b32_e32 v168, 6, v2
	s_nop 0
	v_readfirstlane_b32 s98, v168
	s_lshl_b32 s98, s98, 10
	s_mov_b32 m0, s98
	s_nop 0
	global_load_lds_dwordx4 v4, s[4:5]
	s_add_u32 s4, s4, 0x1000
	s_addc_u32 s5, s5, 0
	s_add_u32 m0, s98, 0x1000
	s_nop 0
	global_load_lds_dwordx4 v4, s[4:5]
	s_add_u32 s4, s4, 0x1000
	s_addc_u32 s5, s5, 0
	s_add_u32 m0, s98, 0x2000
	s_nop 0
	global_load_lds_dwordx4 v4, s[4:5]
	s_add_u32 s4, s4, 0x1000
	s_addc_u32 s5, s5, 0
	s_add_u32 m0, s98, 0x3000
	s_nop 0
	global_load_lds_dwordx4 v4, s[4:5]
	s_add_u32 s4, s4, 0x1000
	s_addc_u32 s5, s5, 0
	s_add_u32 m0, s98, 0x4000
	s_nop 0
	global_load_lds_dwordx4 v4, s[4:5]
	s_add_u32 s4, s4, 0x1000
	s_addc_u32 s5, s5, 0
	s_add_u32 m0, s98, 0x5000
	s_nop 0
	global_load_lds_dwordx4 v4, s[4:5]
	s_add_u32 s4, s4, 0x1000
	s_addc_u32 s5, s5, 0
	s_add_u32 m0, s98, 0x6000
	s_nop 0
	global_load_lds_dwordx4 v4, s[4:5]
	s_add_u32 s4, s4, 0x1000
	s_addc_u32 s5, s5, 0
	s_add_u32 m0, s98, 0x7000
	s_nop 0
	global_load_lds_dwordx4 v4, s[4:5]
	s_add_u32 s4, s4, 0x1000
	s_addc_u32 s5, s5, 0
	s_add_u32 m0, s98, 0x8000
	s_nop 0
	global_load_lds_dwordx4 v4, s[4:5]
	s_add_u32 s4, s4, 0x1000
	s_addc_u32 s5, s5, 0
	s_add_u32 m0, s98, 0x9000
	s_nop 0
	global_load_lds_dwordx4 v4, s[4:5]
	s_add_u32 s4, s4, 0x1000
	s_addc_u32 s5, s5, 0
	s_add_u32 m0, s98, 0xa000
	s_nop 0
	global_load_lds_dwordx4 v4, s[4:5]
	s_add_u32 s4, s4, 0x1000
	s_addc_u32 s5, s5, 0
	s_add_u32 m0, s98, 0xb000
	s_nop 0
	global_load_lds_dwordx4 v4, s[4:5]
	s_add_u32 s4, s4, 0x1000
	s_addc_u32 s5, s5, 0
	s_add_u32 m0, s98, 0xc000
	s_nop 0
	global_load_lds_dwordx4 v4, s[4:5]
	s_add_u32 s4, s4, 0x1000
	s_addc_u32 s5, s5, 0
	s_add_u32 m0, s98, 0xd000
	s_nop 0
	global_load_lds_dwordx4 v4, s[4:5]
	s_add_u32 s4, s4, 0x1000
	s_addc_u32 s5, s5, 0
	s_add_u32 m0, s98, 0xe000
	s_nop 0
	global_load_lds_dwordx4 v4, s[4:5]
	s_add_u32 s4, s4, 0x1000
	s_addc_u32 s5, s5, 0
	s_add_u32 m0, s98, 0xf000
	s_nop 0
	global_load_lds_dwordx4 v4, s[4:5]
	s_waitcnt vmcnt(0)
